# RG-LRU prefetch placement: x row pieces 0-4 requested after conv rows 0-4, pieces 5-10 and the gate piece spread through the gate stage (VGPR running pointer); on top of the S5 blocked scan
# speedup vs baseline: 1.0099x; 1.0017x over previous
; #define LAS __attribute__((address_space(3)))
; __device__ __forceinline__ unsigned cvt_pk_bf16(float lo, float hi) { unsigned r; asm("v_cvt_pk_bf16_f32 %0, %1, %2" : "=v"(r) : "v"(lo), "v"(hi)); return r; }
; __device__ __forceinline__ void lru_item(const Args& a, LAS unsigned char* lds, bool sample, int b, int head, int q, int tid, int lane, int wave) {
;     ...
;         for (int chk = 0; chk < 8; ++chk) {
;             const int R0 = b * SEQ + chk * 256, r0 = rg * 8;
; #pragma unroll
;             for (int rr = 0; rr < 8; ++rr) {
;                 const f32x4 xc = cb + cw0 * xin[rr] + cw1 * xin[rr + 1] + cw2 * xin[rr + 2] + cw3 * xin[rr + 3];
;                 u32x2 w; w.x = cvt_pk_bf16(xc[0], xc[1]); w.y = cvt_pk_bf16(xc[2], xc[3]);
;                 *(LAS u32x2*)(XC + (r0 + rr) * XC_PITCH + 8 * cq) = w;
;                 if ((cq >> 2) == q) *(LAS f32x4*)(XCF + (r0 + rr) * 16 + 4 * (cq & 3)) = xc;
;             }
;             const u32x4 gw = ggn;
;             if (chk < 7) {
;                 const float* p = XL + (size_t)(R0 + 256 + r0 - 3) * DH + cch;
; #pragma unroll
;                 for (int i = 0; i < 11; ++i) xin[i] = *(const f32x4*)(p + (size_t)i * DH);
;                 ggn = *(const u32x4*)(GG + (size_t)(R0 + 256 + er) * DH + ch0 + 8 * eh);
;             }
.LBB0_672:
	v_mov_b32_e32 v228, 0x1000
	v_mov_b32_e32 v229, 0
	v_add_u32_e32 v224, s30, v182
	v_ashrrev_i32_e32 v225, 31, v224
	v_lshlrev_b64 v[224:225], 12, v[224:225]
	v_lshl_add_u64 v[224:225], v[110:111], 0, v[224:225]
	v_pk_fma_f32 v[50:51], v[32:33], v[88:89], v[36:37]
	v_pk_fma_f32 v[52:53], v[30:31], v[86:87], v[34:35]
	v_pk_fma_f32 v[50:51], v[28:29], v[84:85], v[50:51]
	v_pk_fma_f32 v[52:53], v[26:27], v[82:83], v[52:53]
	v_pk_fma_f32 v[50:51], v[24:25], v[80:81], v[50:51]
	v_pk_fma_f32 v[86:87], v[22:23], v[78:79], v[52:53]
	v_pk_fma_f32 v[52:53], v[20:21], v[72:73], v[50:51]
	v_pk_fma_f32 v[50:51], v[18:19], v[70:71], v[86:87]
	v_cvt_pk_bf16_f32 v87, v52, v53
	s_nop 0
	v_cvt_pk_bf16_f32 v86, v50, v51
	ds_write_b64 v175, v[86:87]
	s_and_saveexec_b64 s[36:37], s[8:9]
	v_add_u32_e32 v86, v137, v138
	ds_write_b128 v86, v[50:53] offset:36864
	s_or_b64 exec, exec, s[36:37]
	global_load_dwordx4 v[86:89], v[224:225], off
	v_lshl_add_u64 v[224:225], v[224:225], 0, v[228:229]
	v_pk_fma_f32 v[50:51], v[32:33], v[84:85], v[36:37]
	v_pk_fma_f32 v[52:53], v[30:31], v[82:83], v[34:35]
	v_pk_fma_f32 v[50:51], v[28:29], v[80:81], v[50:51]
	v_pk_fma_f32 v[52:53], v[26:27], v[78:79], v[52:53]
	v_pk_fma_f32 v[50:51], v[24:25], v[72:73], v[50:51]
	v_pk_fma_f32 v[82:83], v[22:23], v[70:71], v[52:53]
	v_pk_fma_f32 v[52:53], v[20:21], v[68:69], v[50:51]
	v_pk_fma_f32 v[50:51], v[18:19], v[66:67], v[82:83]
	v_cvt_pk_bf16_f32 v83, v52, v53
	s_nop 0
	v_cvt_pk_bf16_f32 v82, v50, v51
	ds_write_b64 v176, v[82:83]
	s_and_saveexec_b64 s[36:37], s[8:9]
	v_add_u32_e32 v82, v137, v148
	ds_write_b128 v82, v[50:53] offset:36864
	s_or_b64 exec, exec, s[36:37]
	global_load_dwordx4 v[82:85], v[224:225], off
	v_lshl_add_u64 v[224:225], v[224:225], 0, v[228:229]
	v_pk_fma_f32 v[50:51], v[32:33], v[80:81], v[36:37]
	v_pk_fma_f32 v[52:53], v[30:31], v[78:79], v[34:35]
	v_pk_fma_f32 v[50:51], v[28:29], v[72:73], v[50:51]
	v_pk_fma_f32 v[52:53], v[26:27], v[70:71], v[52:53]
	v_pk_fma_f32 v[50:51], v[24:25], v[68:69], v[50:51]
	v_pk_fma_f32 v[78:79], v[22:23], v[66:67], v[52:53]
	v_pk_fma_f32 v[52:53], v[20:21], v[64:65], v[50:51]
	v_pk_fma_f32 v[50:51], v[18:19], v[62:63], v[78:79]
	v_cvt_pk_bf16_f32 v79, v52, v53
	s_nop 0
	v_cvt_pk_bf16_f32 v78, v50, v51
	ds_write_b64 v176, v[78:79] offset:144
	s_and_saveexec_b64 s[36:37], s[8:9]
	v_add_u32_e32 v78, v137, v149
	ds_write_b128 v78, v[50:53] offset:36864
	s_or_b64 exec, exec, s[36:37]
	global_load_dwordx4 v[78:81], v[224:225], off
	v_lshl_add_u64 v[224:225], v[224:225], 0, v[228:229]
	v_pk_fma_f32 v[50:51], v[32:33], v[72:73], v[36:37]
	v_pk_fma_f32 v[52:53], v[30:31], v[70:71], v[34:35]
	v_pk_fma_f32 v[50:51], v[28:29], v[68:69], v[50:51]
	v_pk_fma_f32 v[52:53], v[26:27], v[66:67], v[52:53]
	v_pk_fma_f32 v[50:51], v[24:25], v[64:65], v[50:51]
	v_pk_fma_f32 v[70:71], v[22:23], v[62:63], v[52:53]
	v_pk_fma_f32 v[52:53], v[20:21], v[60:61], v[50:51]
	v_pk_fma_f32 v[50:51], v[18:19], v[58:59], v[70:71]
	v_cvt_pk_bf16_f32 v71, v52, v53
	s_nop 0
	v_cvt_pk_bf16_f32 v70, v50, v51
	ds_write_b64 v176, v[70:71] offset:288
	s_and_saveexec_b64 s[36:37], s[8:9]
	v_add_u32_e32 v70, v137, v150
	ds_write_b128 v70, v[50:53] offset:36864
	s_or_b64 exec, exec, s[36:37]
	global_load_dwordx4 v[70:73], v[224:225], off
	v_lshl_add_u64 v[224:225], v[224:225], 0, v[228:229]
	v_pk_fma_f32 v[50:51], v[32:33], v[68:69], v[36:37]
	v_pk_fma_f32 v[52:53], v[30:31], v[66:67], v[34:35]
	v_pk_fma_f32 v[50:51], v[28:29], v[64:65], v[50:51]
	v_pk_fma_f32 v[52:53], v[26:27], v[62:63], v[52:53]
	v_pk_fma_f32 v[50:51], v[24:25], v[60:61], v[50:51]
	v_pk_fma_f32 v[66:67], v[22:23], v[58:59], v[52:53]
	v_pk_fma_f32 v[52:53], v[20:21], v[40:41], v[50:51]
	v_pk_fma_f32 v[50:51], v[18:19], v[38:39], v[66:67]
	v_cvt_pk_bf16_f32 v67, v52, v53
	s_nop 0
	v_cvt_pk_bf16_f32 v66, v50, v51
	ds_write_b64 v176, v[66:67] offset:432
	s_and_saveexec_b64 s[36:37], s[8:9]
	v_add_u32_e32 v66, v137, v151
	ds_write_b128 v66, v[50:53] offset:36864
	s_or_b64 exec, exec, s[36:37]
	global_load_dwordx4 v[66:69], v[224:225], off
	v_lshl_add_u64 v[224:225], v[224:225], 0, v[228:229]
	v_pk_fma_f32 v[50:51], v[32:33], v[64:65], v[36:37]
	v_pk_fma_f32 v[52:53], v[30:31], v[62:63], v[34:35]
	v_pk_fma_f32 v[50:51], v[28:29], v[60:61], v[50:51]
	v_pk_fma_f32 v[52:53], v[26:27], v[58:59], v[52:53]
	v_pk_fma_f32 v[50:51], v[24:25], v[40:41], v[50:51]
	v_pk_fma_f32 v[62:63], v[22:23], v[38:39], v[52:53]
	v_pk_fma_f32 v[52:53], v[20:21], v[48:49], v[50:51]
	v_pk_fma_f32 v[50:51], v[18:19], v[46:47], v[62:63]
	v_cvt_pk_bf16_f32 v63, v52, v53
	s_nop 0
	v_cvt_pk_bf16_f32 v62, v50, v51
	ds_write_b64 v176, v[62:63] offset:576
	s_and_saveexec_b64 s[36:37], s[8:9]
	v_add_u32_e32 v62, v137, v152
	ds_write_b128 v62, v[50:53] offset:36864
	s_or_b64 exec, exec, s[36:37]
	v_pk_fma_f32 v[50:51], v[32:33], v[60:61], v[36:37]
	v_pk_fma_f32 v[52:53], v[30:31], v[58:59], v[34:35]
	v_pk_fma_f32 v[50:51], v[28:29], v[40:41], v[50:51]
	v_pk_fma_f32 v[52:53], v[26:27], v[38:39], v[52:53]
	v_pk_fma_f32 v[50:51], v[24:25], v[48:49], v[50:51]
	v_pk_fma_f32 v[58:59], v[22:23], v[46:47], v[52:53]
	v_pk_fma_f32 v[52:53], v[20:21], v[44:45], v[50:51]
	v_pk_fma_f32 v[50:51], v[18:19], v[42:43], v[58:59]
	v_cvt_pk_bf16_f32 v59, v52, v53
	s_nop 0
	v_cvt_pk_bf16_f32 v58, v50, v51
	ds_write_b64 v176, v[58:59] offset:720
	s_and_saveexec_b64 s[36:37], s[8:9]
	v_add_u32_e32 v58, v137, v153
	ds_write_b128 v58, v[50:53] offset:36864
	s_or_b64 exec, exec, s[36:37]
	v_pk_fma_f32 v[40:41], v[32:33], v[40:41], v[36:37]
	v_pk_fma_f32 v[38:39], v[30:31], v[38:39], v[34:35]
	v_pk_fma_f32 v[40:41], v[28:29], v[48:49], v[40:41]
	v_pk_fma_f32 v[38:39], v[26:27], v[46:47], v[38:39]
	v_pk_fma_f32 v[40:41], v[24:25], v[44:45], v[40:41]
	v_pk_fma_f32 v[38:39], v[22:23], v[42:43], v[38:39]
	v_pk_fma_f32 v[40:41], v[20:21], v[56:57], v[40:41]
	v_pk_fma_f32 v[38:39], v[18:19], v[54:55], v[38:39]
	v_cvt_pk_bf16_f32 v43, v40, v41
	s_nop 0
	v_cvt_pk_bf16_f32 v42, v38, v39
	ds_write_b64 v176, v[42:43] offset:864
	s_and_saveexec_b64 s[36:37], s[8:9]
	v_add_u32_e32 v42, v137, v154
	ds_write_b128 v42, v[38:41] offset:36864
	s_or_b64 exec, exec, s[36:37]
	v_add_u32_e32 v186, 0x9000, v155
	v_add_u32_e32 v183, 0xd000, v155
	v_add_u32_e32 v184, 0x9000, v161
	v_add_u32_e32 v185, 0xd000, v161
	s_waitcnt lgkmcnt(0)
	s_barrier
; #define LAS __attribute__((address_space(3)))
; __device__ __forceinline__ float fexp(float x) { return __builtin_amdgcn_exp2f(x * 1.44269504089f); }
; __device__ __forceinline__ float fsigmoid(float x) { return __builtin_amdgcn_rcpf(1.0f + fexp(-x)); }
; __device__ __forceinline__ void lru_item(const Args& a, LAS unsigned char* lds, bool sample, int b, int head, int q, int tid, int lane, int wave) {
;     ...
; #pragma unroll
;             for (int tt = 0; tt < 2; ++tt) {
;                 const int tile = 2 * wave + tt;
;                 f32x4 ar = (f32x4){0.f, 0.f, 0.f, 0.f}, ax = ar;
; #pragma unroll
;                 for (int ks = 0; ks < 2; ++ks) {
;                     const bf16x8 af = *(const LAS bf16x8*)(XC + (16 * tile + fr) * XC_PITCH + 64 * ks + 16 * fq);
;                     ar = __builtin_amdgcn_mfma_f32_16x16x32_bf16(af, Bf[0][ks], ar, 0, 0, 0);
;                     ax = __builtin_amdgcn_mfma_f32_16x16x32_bf16(af, Bf[1][ks], ax, 0, 0, 0);
;                 }
; #pragma unroll
;                 for (int r4 = 0; r4 < 4; ++r4) {
;                     const int rr = 16 * tile + 4 * fq + r4;
;                     const float xcv = XCF[rr * 16 + fr];
;                     const float rg_ = fsigmoid(ar[r4] + ba), ig = fsigmoid(ax[r4] + bx_);
;                     const float la = -8.0f * rg_ * spl;
;                     const float av = fexp(la); AA[rr * 16 + fr] = av; BX[rr * 16 + fr] = __builtin_amdgcn_sqrtf(fmaxf(fmaf(-av, av, 1.0f), 0.f)) * (ig * xcv);
;                 }
;             }
;             __syncthreads();
	ds_read_b128 v[118:121], v177
	ds_read_b32 v108, v155 offset:36992
	ds_read_b128 v[126:129], v177 offset:64
	s_waitcnt lgkmcnt(2)
	v_mfma_f32_16x16x32_bf16 v[122:125], v[118:121], v[2:5], 0
	v_mov_b32_e32 v187, v140
	s_waitcnt lgkmcnt(0)
	v_mfma_f32_16x16x32_bf16 v[122:125], v[126:129], v[14:17], v[122:125]
	v_mfma_f32_16x16x32_bf16 v[118:121], v[118:121], v[6:9], 0
	s_nop 6
	v_add_f32_e32 v122, v97, v122
	v_mul_f32_e32 v122, 0xbfb8aa3b, v122
	v_exp_f32_e32 v122, v122
	v_mfma_f32_16x16x32_bf16 v[118:121], v[126:129], v[10:13], v[118:121]
	ds_read2_b32 v[126:127], v186 offset1:16
	v_add_f32_e32 v123, v97, v123
	v_add_f32_e32 v122, 1.0, v122
	v_rcp_f32_e32 v122, v122
	v_mul_f32_e32 v123, 0xbfb8aa3b, v123
	s_nop 2
	v_add_f32_e32 v118, v93, v118
	v_mul_f32_e32 v118, 0xbfb8aa3b, v118
	v_mul_f32_e32 v122, 0xc1000000, v122
	v_mul_f32_e32 v122, v180, v122
	v_mul_f32_e32 v122, 0x3fb8aa3b, v122
	global_load_dwordx4 v[62:65], v[224:225], off
	v_lshl_add_u64 v[224:225], v[224:225], 0, v[228:229]
	v_exp_f32_e32 v118, v118
	v_exp_f32_e32 v122, v122
	v_exp_f32_e32 v123, v123
	v_add_f32_e32 v119, v93, v119
	v_add_f32_e32 v118, 1.0, v118
	v_fma_f32 v128, -v122, v122, 1.0
	v_rcp_f32_e32 v118, v118
	v_max_f32_e32 v128, 0, v128
	v_sqrt_f32_e32 v128, v128
	v_mul_f32_e32 v119, 0xbfb8aa3b, v119
	s_waitcnt lgkmcnt(0)
	v_mul_f32_e32 v118, v126, v118
	v_exp_f32_e32 v119, v119
	v_mul_f32_e32 v118, v118, v128
	ds_write_b32 v156, v118
	v_add_f32_e32 v118, 1.0, v123
	v_rcp_f32_e32 v118, v118
	v_add_f32_e32 v124, v97, v124
	v_add_f32_e32 v119, 1.0, v119
	v_mul_f32_e32 v124, 0xbfb8aa3b, v124
	v_mul_f32_e32 v118, 0xc1000000, v118
	v_mul_f32_e32 v118, v180, v118
	v_mul_f32_e32 v118, 0x3fb8aa3b, v118
	v_exp_f32_e32 v118, v118
	v_rcp_f32_e32 v119, v119
	global_load_dwordx4 v[58:61], v[224:225], off
	v_lshl_add_u64 v[224:225], v[224:225], 0, v[228:229]
	v_exp_f32_e32 v124, v124
	v_add_f32_e32 v120, v93, v120
	v_fma_f32 v123, -v118, v118, 1.0
	ds_write2_b32 v183, v122, v118 offset1:16
	v_mul_f32_e32 v118, v127, v119
	v_add_f32_e32 v119, 1.0, v124
	v_rcp_f32_e32 v119, v119
	v_max_f32_e32 v123, 0, v123
	v_sqrt_f32_e32 v123, v123
	v_mul_f32_e32 v120, 0xbfb8aa3b, v120
	v_mul_f32_e32 v119, 0xc1000000, v119
	v_mul_f32_e32 v119, v180, v119
	v_mul_f32_e32 v119, 0x3fb8aa3b, v119
	v_exp_f32_e32 v120, v120
	v_exp_f32_e32 v119, v119
	v_mul_f32_e32 v118, v118, v123
	ds_write_b32 v157, v118
	v_add_f32_e32 v118, 1.0, v120
	ds_write_b32 v155, v119 offset:53376
	v_fma_f32 v119, -v119, v119, 1.0
	v_rcp_f32_e32 v118, v118
	v_max_f32_e32 v119, 0, v119
	v_add_f32_e32 v120, v97, v125
	v_sqrt_f32_e32 v119, v119
	v_mul_f32_e32 v120, 0xbfb8aa3b, v120
	global_load_dwordx4 v[38:41], v[224:225], off
	v_lshl_add_u64 v[224:225], v[224:225], 0, v[228:229]
	v_exp_f32_e32 v120, v120
	v_mul_f32_e32 v108, v118, v108
	v_mul_f32_e32 v108, v108, v119
	ds_write_b32 v158, v108
	v_add_f32_e32 v108, 1.0, v120
	v_rcp_f32_e32 v108, v108
	v_add_f32_e32 v118, v93, v121
	v_mul_f32_e32 v118, 0xbfb8aa3b, v118
	v_exp_f32_e32 v118, v118
	v_mul_f32_e32 v108, 0xc1000000, v108
	v_mul_f32_e32 v108, v180, v108
	v_mul_f32_e32 v108, 0x3fb8aa3b, v108
	v_exp_f32_e32 v108, v108
	ds_read_b32 v119, v159 offset:36864
	v_add_f32_e32 v118, 1.0, v118
	v_rcp_f32_e32 v118, v118
	v_fma_f32 v120, -v108, v108, 1.0
	v_max_f32_e32 v120, 0, v120
	v_sqrt_f32_e32 v120, v120
	ds_write_b32 v159, v108 offset:53248
	s_waitcnt lgkmcnt(1)
	v_mul_f32_e32 v108, v118, v119
	v_mul_f32_e32 v108, v108, v120
	ds_write_b32 v160, v108
	ds_read_b128 v[118:121], v178
	global_load_dwordx4 v[46:49], v[224:225], off
	v_lshl_add_u64 v[224:225], v[224:225], 0, v[228:229]
	ds_read_b32 v108, v161 offset:36992
	ds_read_b128 v[126:129], v178 offset:64
	s_waitcnt lgkmcnt(2)
	v_mfma_f32_16x16x32_bf16 v[122:125], v[118:121], v[2:5], 0
	s_waitcnt lgkmcnt(0)
	v_mfma_f32_16x16x32_bf16 v[122:125], v[126:129], v[14:17], v[122:125]
	v_mfma_f32_16x16x32_bf16 v[118:121], v[118:121], v[6:9], 0
	s_nop 6
	v_add_f32_e32 v122, v97, v122
	v_mul_f32_e32 v122, 0xbfb8aa3b, v122
	v_exp_f32_e32 v122, v122
	v_mfma_f32_16x16x32_bf16 v[118:121], v[126:129], v[10:13], v[118:121]
	ds_read2_b32 v[126:127], v184 offset1:16
	v_add_f32_e32 v123, v97, v123
	v_add_f32_e32 v122, 1.0, v122
	v_rcp_f32_e32 v122, v122
	v_mul_f32_e32 v123, 0xbfb8aa3b, v123
	s_nop 2
	v_add_f32_e32 v118, v93, v118
	v_mul_f32_e32 v118, 0xbfb8aa3b, v118
	v_mul_f32_e32 v122, 0xc1000000, v122
	v_mul_f32_e32 v122, v180, v122
	v_mul_f32_e32 v122, 0x3fb8aa3b, v122
	v_exp_f32_e32 v118, v118
	global_load_dwordx4 v[42:45], v[224:225], off
	v_lshl_add_u64 v[224:225], v[224:225], 0, v[228:229]
	v_exp_f32_e32 v122, v122
	v_exp_f32_e32 v123, v123
	v_add_f32_e32 v119, v93, v119
	v_add_f32_e32 v118, 1.0, v118
	v_fma_f32 v128, -v122, v122, 1.0
	v_rcp_f32_e32 v118, v118
	v_max_f32_e32 v128, 0, v128
	v_sqrt_f32_e32 v128, v128
	v_mul_f32_e32 v119, 0xbfb8aa3b, v119
	s_waitcnt lgkmcnt(0)
; #define LAS __attribute__((address_space(3)))
; __device__ __forceinline__ float fexp(float x) { return __builtin_amdgcn_exp2f(x * 1.44269504089f); }
; __device__ __forceinline__ float fsigmoid(float x) { return __builtin_amdgcn_rcpf(1.0f + fexp(-x)); }
; __device__ __forceinline__ void lru_item(const Args& a, LAS unsigned char* lds, bool sample, int b, int head, int q, int tid, int lane, int wave) {
;     ...
; #pragma unroll
;             for (int tt = 0; tt < 2; ++tt) {
;                 const int tile = 2 * wave + tt;
;                 f32x4 ar = (f32x4){0.f, 0.f, 0.f, 0.f}, ax = ar;
; #pragma unroll
;                 for (int ks = 0; ks < 2; ++ks) {
;                     const bf16x8 af = *(const LAS bf16x8*)(XC + (16 * tile + fr) * XC_PITCH + 64 * ks + 16 * fq);
;                     ar = __builtin_amdgcn_mfma_f32_16x16x32_bf16(af, Bf[0][ks], ar, 0, 0, 0);
;                     ax = __builtin_amdgcn_mfma_f32_16x16x32_bf16(af, Bf[1][ks], ax, 0, 0, 0);
;                 }
; #pragma unroll
;                 for (int r4 = 0; r4 < 4; ++r4) {
;                     const int rr = 16 * tile + 4 * fq + r4;
;                     const float xcv = XCF[rr * 16 + fr];
;                     const float rg_ = fsigmoid(ar[r4] + ba), ig = fsigmoid(ax[r4] + bx_);
;                     const float la = -8.0f * rg_ * spl;
;                     const float av = fexp(la); AA[rr * 16 + fr] = av; BX[rr * 16 + fr] = __builtin_amdgcn_sqrtf(fmaxf(fmaf(-av, av, 1.0f), 0.f)) * (ig * xcv);
;                 }
;             }
;             __syncthreads();
;             const int sn = tid & 15, sg = tid >> 4;
;             float av[8], bv[8];
;             const LAS float* ap = AA + (8 * sg) * 16 + sn; LAS float* bp = BX + (8 * sg) * 16 + sn;
;             asm volatile("" : "+v"(ap), "+v"(bp));
;             { float P = 1.f, h = 0.f;
; #pragma unroll
;               for (int i = 0; i < 8; ++i) { av[i] = ap[i * 16]; bv[i] = bp[i * 16]; }
; #pragma unroll
;               for (int i = 0; i < 8; ++i) { h = av[i] * h + bv[i]; P *= av[i]; }
;               SEGP[tid] = P; SEGH[tid] = h; }
	v_mul_f32_e32 v118, v126, v118
	v_exp_f32_e32 v119, v119
	v_mul_f32_e32 v118, v118, v128
	ds_write_b32 v164, v118
	v_add_f32_e32 v118, 1.0, v123
	v_rcp_f32_e32 v118, v118
	v_add_f32_e32 v124, v97, v124
	v_add_f32_e32 v119, 1.0, v119
	v_mul_f32_e32 v124, 0xbfb8aa3b, v124
	v_mul_f32_e32 v118, 0xc1000000, v118
	v_mul_f32_e32 v118, v180, v118
	v_mul_f32_e32 v118, 0x3fb8aa3b, v118
	v_exp_f32_e32 v118, v118
	v_rcp_f32_e32 v119, v119
	v_exp_f32_e32 v124, v124
	global_load_dwordx4 v[54:57], v[224:225], off
	v_add_f32_e32 v120, v93, v120
	v_fma_f32 v123, -v118, v118, 1.0
	ds_write2_b32 v185, v122, v118 offset1:16
	v_mul_f32_e32 v118, v127, v119
	v_add_f32_e32 v119, 1.0, v124
	v_rcp_f32_e32 v119, v119
	v_max_f32_e32 v123, 0, v123
	v_sqrt_f32_e32 v123, v123
	v_mul_f32_e32 v120, 0xbfb8aa3b, v120
	v_mul_f32_e32 v119, 0xc1000000, v119
	v_mul_f32_e32 v119, v180, v119
	v_mul_f32_e32 v119, 0x3fb8aa3b, v119
	v_exp_f32_e32 v120, v120
	v_exp_f32_e32 v119, v119
	v_mul_f32_e32 v118, v118, v123
	ds_write_b32 v165, v118
	v_add_f32_e32 v118, 1.0, v120
	ds_write_b32 v161, v119 offset:53376
	v_fma_f32 v119, -v119, v119, 1.0
	v_rcp_f32_e32 v118, v118
	v_max_f32_e32 v119, 0, v119
	v_add_f32_e32 v120, v97, v125
	v_sqrt_f32_e32 v119, v119
	v_mul_f32_e32 v120, 0xbfb8aa3b, v120
	v_exp_f32_e32 v120, v120
	v_add_u32_e32 v226, s30, v181
	v_ashrrev_i32_e32 v227, 31, v226
	v_lshlrev_b64 v[226:227], 11, v[226:227]
	v_lshl_add_u64 v[226:227], v[112:113], 0, v[226:227]
	global_load_dwordx4 v[50:53], v[226:227], off
	v_mul_f32_e32 v108, v118, v108
	v_mul_f32_e32 v108, v108, v119
	ds_write_b32 v166, v108
	v_add_f32_e32 v108, 1.0, v120
	v_rcp_f32_e32 v108, v108
	v_add_f32_e32 v118, v93, v121
	v_mul_f32_e32 v118, 0xbfb8aa3b, v118
	v_exp_f32_e32 v118, v118
	v_mul_f32_e32 v108, 0xc1000000, v108
	v_mul_f32_e32 v108, v180, v108
	v_mul_f32_e32 v108, 0x3fb8aa3b, v108
	v_exp_f32_e32 v108, v108
	ds_read_b32 v119, v167 offset:36864
	v_add_f32_e32 v118, 1.0, v118
	v_rcp_f32_e32 v118, v118
	v_fma_f32 v120, -v108, v108, 1.0
	v_max_f32_e32 v120, 0, v120
	v_sqrt_f32_e32 v120, v120
	ds_write_b32 v167, v108 offset:53248
	s_waitcnt lgkmcnt(1)
	v_mul_f32_e32 v108, v118, v119
	v_mul_f32_e32 v108, v108, v120
	ds_write_b32 v168, v108
	v_mov_b32_e32 v108, v139
	s_waitcnt lgkmcnt(0)
	s_barrier
	ds_read2_b32 v[132:133], v108 offset1:16
	ds_read2_b32 v[130:131], v187 offset1:16
	ds_read2_b32 v[128:129], v108 offset0:32 offset1:48
	ds_read2_b32 v[126:127], v187 offset0:32 offset1:48
	ds_read2_b32 v[124:125], v108 offset0:64 offset1:80
	ds_read2_b32 v[122:123], v187 offset0:64 offset1:80
	ds_read2_b32 v[118:119], v108 offset0:96 offset1:112
	ds_read2_b32 v[120:121], v187 offset0:96 offset1:112
	s_waitcnt lgkmcnt(6)
	v_fma_f32 v108, 0, v132, v130
	v_mul_f32_e32 v188, v132, v133
	v_fma_f32 v108, v108, v133, v131
	s_waitcnt lgkmcnt(5)
	v_mul_f32_e32 v188, v188, v128
	s_waitcnt lgkmcnt(4)
	v_fma_f32 v108, v108, v128, v126
	v_mul_f32_e32 v188, v188, v129
	v_fma_f32 v108, v108, v129, v127
	s_waitcnt lgkmcnt(3)
	v_mul_f32_e32 v188, v188, v124
	s_waitcnt lgkmcnt(2)
	v_fma_f32 v108, v108, v124, v122
	v_mul_f32_e32 v188, v188, v125
	v_fma_f32 v108, v108, v125, v123
	s_waitcnt lgkmcnt(1)
	v_mul_f32_e32 v188, v188, v118
	s_waitcnt lgkmcnt(0)
	v_fma_f32 v108, v108, v118, v120
	v_mul_f32_e32 v188, v188, v119
	v_fma_f32 v108, v108, v119, v121
	ds_write_b32 v141, v188
	ds_write_b32 v142, v108
	s_waitcnt lgkmcnt(0)
	s_barrier
	s_and_saveexec_b64 s[36:37], s[18:19]
	s_cbranch_execz .LBB0_690
; #define LAS __attribute__((address_space(3)))
; __device__ __forceinline__ void lru_item(const Args& a, LAS unsigned char* lds, bool sample, int b, int head, int q, int tid, int lane, int wave) {
;     ...
;             if (wave == 0 && lane < 16) {
;                 const LAS float* pp = SEGP + lane; const LAS float* hp = SEGH + lane; LAS float* cp = CAR + lane;
;                 asm volatile("" : "+v"(pp), "+v"(hp), "+v"(cp));
;                 float run = hcar;
; #pragma unroll
;                 for (int h2 = 0; h2 < 2; ++h2) {
;                     float sp_[16], sh_[16];
; #pragma unroll
;                     for (int s2 = 0; s2 < 16; ++s2) { sp_[s2] = pp[(16 * h2 + s2) * 16]; sh_[s2] = hp[(16 * h2 + s2) * 16]; }
; #pragma unroll
;                     for (int s2 = 0; s2 < 16; ++s2) { cp[(16 * h2 + s2) * 16] = run; run = sp_[s2] * run + sh_[s2]; }
;                 }
;                 hcar = run;
;             }
	v_mov_b32_e32 v108, v144
	v_mov_b32_e32 v211, v143
	v_mov_b32_e32 v222, v145
	ds_read2_b32 v[188:189], v211 offset1:16
	ds_read2_b32 v[190:191], v108 offset1:16
	ds_read2_b32 v[192:193], v211 offset0:32 offset1:48
	ds_read2_b32 v[194:195], v108 offset0:32 offset1:48
	ds_read2_b32 v[196:197], v211 offset0:64 offset1:80
	ds_read2_b32 v[198:199], v108 offset0:64 offset1:80
	ds_read2_b32 v[200:201], v211 offset0:96 offset1:112
	ds_read2_b32 v[202:203], v108 offset0:96 offset1:112
	ds_read2_b32 v[204:205], v211 offset0:128 offset1:144
	ds_read2_b32 v[206:207], v108 offset0:128 offset1:144
	ds_read2_b32 v[208:209], v211 offset0:160 offset1:176
	ds_read2_b32 v[212:213], v108 offset0:160 offset1:176
	ds_read2_b32 v[214:215], v211 offset0:192 offset1:208
	ds_read2_b32 v[216:217], v108 offset0:192 offset1:208
	ds_read2_b32 v[218:219], v211 offset0:224 offset1:240
	ds_read2_b32 v[220:221], v108 offset0:224 offset1:240
	s_waitcnt lgkmcnt(14)
	v_fma_f32 v188, v109, v188, v190
	v_fmac_f32_e32 v191, v188, v189
	ds_write2_b32 v222, v109, v188 offset1:16
	s_waitcnt lgkmcnt(13)
	v_fma_f32 v109, v191, v192, v194
	v_fmac_f32_e32 v195, v109, v193
	ds_write2_b32 v222, v191, v109 offset0:32 offset1:48
	s_waitcnt lgkmcnt(12)
	v_fma_f32 v109, v195, v196, v198
	v_fmac_f32_e32 v199, v109, v197
	ds_write2_b32 v222, v195, v109 offset0:64 offset1:80
	s_waitcnt lgkmcnt(11)
	v_fma_f32 v109, v199, v200, v202
	v_fmac_f32_e32 v203, v109, v201
	ds_write2_b32 v222, v199, v109 offset0:96 offset1:112
	s_waitcnt lgkmcnt(10)
	v_fma_f32 v109, v203, v204, v206
	v_fmac_f32_e32 v207, v109, v205
	ds_write2_b32 v222, v203, v109 offset0:128 offset1:144
	s_waitcnt lgkmcnt(9)
	v_fma_f32 v109, v207, v208, v212
	v_fmac_f32_e32 v213, v109, v209
	ds_write2_b32 v222, v207, v109 offset0:160 offset1:176
	s_waitcnt lgkmcnt(8)
	v_fma_f32 v109, v213, v214, v216
	v_fmac_f32_e32 v217, v109, v215
	ds_write2_b32 v222, v213, v109 offset0:192 offset1:208
	s_waitcnt lgkmcnt(7)
	v_fma_f32 v109, v217, v218, v220
	ds_write2_b32 v222, v217, v109 offset0:224 offset1:240
	v_fmac_f32_e32 v221, v109, v219
	v_add_u32_e32 v109, 0x400, v211
	ds_read2_b32 v[188:189], v109 offset1:16
	v_add_u32_e32 v108, 0x400, v108
	ds_read2_b32 v[190:191], v108 offset1:16
	ds_read2_b32 v[192:193], v109 offset0:32 offset1:48
	ds_read2_b32 v[194:195], v108 offset0:32 offset1:48
	ds_read2_b32 v[196:197], v109 offset0:64 offset1:80
	ds_read2_b32 v[198:199], v108 offset0:64 offset1:80
	ds_read2_b32 v[200:201], v109 offset0:96 offset1:112
	ds_read2_b32 v[202:203], v108 offset0:96 offset1:112
	ds_read2_b32 v[204:205], v109 offset0:128 offset1:144
	ds_read2_b32 v[206:207], v108 offset0:128 offset1:144
	ds_read2_b32 v[208:209], v109 offset0:160 offset1:176
	ds_read2_b32 v[212:213], v108 offset0:160 offset1:176
	ds_read2_b32 v[214:215], v109 offset0:192 offset1:208
	ds_read2_b32 v[216:217], v108 offset0:192 offset1:208
	ds_read2_b32 v[218:219], v109 offset0:224 offset1:240
	ds_read2_b32 v[108:109], v108 offset0:224 offset1:240
	s_waitcnt lgkmcnt(14)
	v_fma_f32 v188, v221, v188, v190
	v_add_u32_e32 v190, 0x400, v222
	v_fmac_f32_e32 v191, v188, v189
	ds_write2_b32 v190, v221, v188 offset1:16
	s_waitcnt lgkmcnt(13)
	v_fma_f32 v188, v191, v192, v194
	v_fmac_f32_e32 v195, v188, v193
	ds_write2_b32 v190, v191, v188 offset0:32 offset1:48
	s_waitcnt lgkmcnt(12)
	v_fma_f32 v188, v195, v196, v198
	v_fmac_f32_e32 v199, v188, v197
	ds_write2_b32 v190, v195, v188 offset0:64 offset1:80
	s_waitcnt lgkmcnt(11)
	v_fma_f32 v188, v199, v200, v202
	v_fmac_f32_e32 v203, v188, v201
	ds_write2_b32 v190, v199, v188 offset0:96 offset1:112
	s_waitcnt lgkmcnt(10)
	v_fma_f32 v188, v203, v204, v206
	v_fmac_f32_e32 v207, v188, v205
	ds_write2_b32 v190, v203, v188 offset0:128 offset1:144
	s_waitcnt lgkmcnt(9)
	v_fma_f32 v188, v207, v208, v212
	v_fmac_f32_e32 v213, v188, v209
	ds_write2_b32 v190, v207, v188 offset0:160 offset1:176
	s_waitcnt lgkmcnt(8)
	v_fma_f32 v188, v213, v214, v216
	v_fmac_f32_e32 v217, v188, v215
	s_waitcnt lgkmcnt(6)
	v_fma_f32 v108, v217, v218, v108
	v_fmac_f32_e32 v109, v108, v219
	ds_write2_b32 v190, v213, v188 offset0:192 offset1:208
	ds_write2_b32 v190, v217, v108 offset0:224 offset1:240
